# loop-edge edits in the 10 GEMM K-loops: relax flag taken from the scalar mask (no v_cndmask/readfirstlane), strict-wait path falls through in SP1, single taken branch in SP2; on top of non-scaled MFMA
# baseline (speedup 1.0000x reference)
.LBB0_251:
	s_cmp_eq_u32 s30, 0
	s_cselect_b64 s[34:35], -1, 0
	s_and_b64 s[34:35], s[0:1], s[34:35]
	s_and_b32 s34, s34, 1
	ds_read_b128 v[26:29], v232
	ds_read_b128 v[30:33], v232 offset:1024
	ds_read_b128 v[18:21], v232 offset:2048
	ds_read_b128 v[22:25], v232 offset:3072
	ds_read_b128 v[10:13], v233
	ds_read_b128 v[14:17], v233 offset:1024
	ds_read_b128 v[2:5], v233 offset:2048
	ds_read_b128 v[6:9], v233 offset:3072
	v_lshl_add_u64 v[222:223], v[220:221], 0, s[30:31]
	s_add_i32 m0, s49, 0xc000
	ds_read_b128 v[58:61], v234
	ds_read_b128 v[62:65], v234 offset:1024
	ds_read_b128 v[50:53], v234 offset:2048
	ds_read_b128 v[54:57], v234 offset:3072
	ds_read_b128 v[42:45], v234 offset:4096
	ds_read_b128 v[46:49], v234 offset:5120
	ds_read_b128 v[34:37], v234 offset:6144
	ds_read_b128 v[38:41], v234 offset:7168
	global_load_lds_dwordx4 v[222:223], off
	v_lshl_add_u64 v[222:223], v[218:219], 0, s[30:31]
	s_add_i32 m0, s49, 0xe000
	s_cmp_lg_u32 s34, 0
	global_load_lds_dwordx4 v[222:223], off
	s_cselect_b64 s[38:39], -1, 0
	s_cmp_eq_u32 s34, 0
	s_cbranch_scc0 .Lrx1_251

.Lrx1_251:
	s_waitcnt vmcnt(16)
	s_branch .LBB0_254

.LBB0_886:
	s_cmp_eq_u32 s6, 0
	s_cselect_b64 s[26:27], -1, 0
	s_and_b64 s[26:27], s[0:1], s[26:27]
	s_and_b32 s26, s26, 1
	ds_read_b128 v[26:29], v224
	ds_read_b128 v[30:33], v224 offset:1024
	ds_read_b128 v[18:21], v224 offset:2048
	ds_read_b128 v[22:25], v224 offset:3072
	ds_read_b128 v[10:13], v225
	ds_read_b128 v[14:17], v225 offset:1024
	ds_read_b128 v[2:5], v225 offset:2048
	ds_read_b128 v[6:9], v225 offset:3072
	v_lshl_add_u64 v[214:215], v[212:213], 0, s[6:7]
	s_add_i32 m0, s40, 0xc000
	ds_read_b128 v[58:61], v226
	ds_read_b128 v[62:65], v226 offset:1024
	ds_read_b128 v[50:53], v226 offset:2048
	ds_read_b128 v[54:57], v226 offset:3072
	ds_read_b128 v[42:45], v226 offset:4096
	ds_read_b128 v[46:49], v226 offset:5120
	ds_read_b128 v[34:37], v226 offset:6144
	ds_read_b128 v[38:41], v226 offset:7168
	global_load_lds_dwordx4 v[214:215], off
	v_lshl_add_u64 v[214:215], v[210:211], 0, s[6:7]
	s_add_i32 m0, s40, 0xe000
	s_cmp_lg_u32 s26, 0
	global_load_lds_dwordx4 v[214:215], off
	s_cselect_b64 s[30:31], -1, 0
	s_cmp_eq_u32 s26, 0
	s_cbranch_scc0 .Lrx1_886

.Lrx1_886:
	s_waitcnt vmcnt(24)
	s_branch .LBB0_889

.LBB0_1063:
	s_cmp_eq_u32 s36, 0
	s_cselect_b64 s[38:39], -1, 0
	s_and_b64 s[38:39], s[34:35], s[38:39]
	s_and_b32 s38, s38, 1
	ds_read_b128 v[26:29], v224
	ds_read_b128 v[30:33], v224 offset:1024
	ds_read_b128 v[18:21], v224 offset:2048
	ds_read_b128 v[22:25], v224 offset:3072
	ds_read_b128 v[10:13], v225
	ds_read_b128 v[14:17], v225 offset:1024
	ds_read_b128 v[2:5], v225 offset:2048
	ds_read_b128 v[6:9], v225 offset:3072
	v_lshl_add_u64 v[214:215], v[212:213], 0, s[36:37]
	s_add_i32 m0, s54, 0xc000
	ds_read_b128 v[58:61], v226
	ds_read_b128 v[62:65], v226 offset:1024
	ds_read_b128 v[50:53], v226 offset:2048
	ds_read_b128 v[54:57], v226 offset:3072
	ds_read_b128 v[42:45], v226 offset:4096
	ds_read_b128 v[46:49], v226 offset:5120
	ds_read_b128 v[34:37], v226 offset:6144
	ds_read_b128 v[38:41], v226 offset:7168
	global_load_lds_dwordx4 v[214:215], off
	v_lshl_add_u64 v[214:215], v[210:211], 0, s[36:37]
	s_add_i32 m0, s54, 0xe000
	s_cmp_lg_u32 s38, 0
	global_load_lds_dwordx4 v[214:215], off
	s_cselect_b64 s[42:43], -1, 0
	s_cmp_eq_u32 s38, 0
	s_cbranch_scc0 .Lrx1_1063

.LBB0_1226:
	s_cmp_eq_u32 s50, 0
	s_cselect_b64 s[52:53], -1, 0
	s_and_b64 s[52:53], s[48:49], s[52:53]
	s_and_b32 s52, s52, 1
	ds_read_b128 v[82:85], v228
	ds_read_b128 v[86:89], v228 offset:1024
	ds_read_b128 v[90:93], v228 offset:2048
	ds_read_b128 v[94:97], v228 offset:3072
	ds_read_b128 v[66:69], v229
	ds_read_b128 v[70:73], v229 offset:1024
	ds_read_b128 v[74:77], v229 offset:2048
	ds_read_b128 v[78:81], v229 offset:3072
	v_lshl_add_u64 v[220:221], v[218:219], 0, s[50:51]
	s_add_i32 m0, s68, 0xc000
	ds_read_b128 v[186:189], v231
	ds_read_b128 v[190:193], v231 offset:1024
	ds_read_b128 v[178:181], v231 offset:2048
	ds_read_b128 v[182:185], v231 offset:3072
	ds_read_b128 v[170:173], v231 offset:4096
	ds_read_b128 v[174:177], v231 offset:5120
	ds_read_b128 v[162:165], v231 offset:6144
	ds_read_b128 v[166:169], v231 offset:7168
	global_load_lds_dwordx4 v[220:221], off
	v_lshl_add_u64 v[220:221], v[216:217], 0, s[50:51]
	s_add_i32 m0, s68, 0xe000
	s_cmp_lg_u32 s52, 0
	global_load_lds_dwordx4 v[220:221], off
	s_cselect_b64 s[56:57], -1, 0
	s_cmp_eq_u32 s52, 0
	s_cbranch_scc0 .Lrx1_1226

.LBB0_1398:
	s_cmp_eq_u32 s26, 0
	s_cselect_b64 s[28:29], -1, 0
	s_and_b64 s[28:29], s[24:25], s[28:29]
	s_and_b32 s28, s28, 1
	ds_read_b128 v[146:149], v224
	ds_read_b128 v[150:153], v224 offset:1024
	ds_read_b128 v[154:157], v224 offset:2048
	ds_read_b128 v[158:161], v224 offset:3072
	ds_read_b128 v[130:133], v225
	ds_read_b128 v[134:137], v225 offset:1024
	ds_read_b128 v[138:141], v225 offset:2048
	ds_read_b128 v[142:145], v225 offset:3072
	v_lshl_add_u64 v[214:215], v[212:213], 0, s[26:27]
	s_add_i32 m0, s48, 0xc000
	ds_read_b128 v[186:189], v226
	ds_read_b128 v[190:193], v226 offset:1024
	ds_read_b128 v[178:181], v226 offset:2048
	ds_read_b128 v[182:185], v226 offset:3072
	ds_read_b128 v[170:173], v226 offset:4096
	ds_read_b128 v[174:177], v226 offset:5120
	ds_read_b128 v[162:165], v226 offset:6144
	ds_read_b128 v[166:169], v226 offset:7168
	global_load_lds_dwordx4 v[214:215], off
	v_lshl_add_u64 v[214:215], v[210:211], 0, s[26:27]
	s_add_i32 m0, s48, 0xe000
	s_cmp_lg_u32 s28, 0
	global_load_lds_dwordx4 v[214:215], off
	s_cselect_b64 s[34:35], -1, 0
	s_cmp_eq_u32 s28, 0
	s_cbranch_scc0 .Lrx1_1398

.LBB0_2410:
	s_cmp_eq_u32 s36, 0
	s_cselect_b64 s[38:39], -1, 0
	s_and_b64 s[38:39], s[34:35], s[38:39]
	s_and_b32 s38, s38, 1
	ds_read_b128 v[26:29], v224
	ds_read_b128 v[30:33], v224 offset:1024
	ds_read_b128 v[18:21], v224 offset:2048
	ds_read_b128 v[22:25], v224 offset:3072
	ds_read_b128 v[10:13], v225
	ds_read_b128 v[14:17], v225 offset:1024
	ds_read_b128 v[2:5], v225 offset:2048
	ds_read_b128 v[6:9], v225 offset:3072
	v_lshl_add_u64 v[214:215], v[212:213], 0, s[36:37]
	s_add_i32 m0, s53, 0xc000
	ds_read_b128 v[58:61], v226
	ds_read_b128 v[62:65], v226 offset:1024
	ds_read_b128 v[50:53], v226 offset:2048
	ds_read_b128 v[54:57], v226 offset:3072
	ds_read_b128 v[42:45], v226 offset:4096
	ds_read_b128 v[46:49], v226 offset:5120
	ds_read_b128 v[34:37], v226 offset:6144
	ds_read_b128 v[38:41], v226 offset:7168
	global_load_lds_dwordx4 v[214:215], off
	v_lshl_add_u64 v[214:215], v[210:211], 0, s[36:37]
	s_add_i32 m0, s53, 0xe000
	s_cmp_lg_u32 s38, 0
	global_load_lds_dwordx4 v[214:215], off
	s_cselect_b64 s[42:43], -1, 0
	s_cmp_eq_u32 s38, 0
	s_cbranch_scc0 .Lrx1_2410

.LBB0_2742:
	s_cmp_eq_u32 s26, 0
	s_cselect_b64 s[28:29], -1, 0
	s_and_b64 s[28:29], s[24:25], s[28:29]
	s_and_b32 s28, s28, 1
	ds_read_b128 v[146:149], v224
	ds_read_b128 v[150:153], v224 offset:1024
	ds_read_b128 v[154:157], v224 offset:2048
	ds_read_b128 v[158:161], v224 offset:3072
	ds_read_b128 v[130:133], v225
	ds_read_b128 v[134:137], v225 offset:1024
	ds_read_b128 v[138:141], v225 offset:2048
	ds_read_b128 v[142:145], v225 offset:3072
	v_lshl_add_u64 v[214:215], v[212:213], 0, s[26:27]
	s_add_i32 m0, s44, 0xc000
	ds_read_b128 v[186:189], v226
	ds_read_b128 v[190:193], v226 offset:1024
	ds_read_b128 v[178:181], v226 offset:2048
	ds_read_b128 v[182:185], v226 offset:3072
	ds_read_b128 v[170:173], v226 offset:4096
	ds_read_b128 v[174:177], v226 offset:5120
	ds_read_b128 v[162:165], v226 offset:6144
	ds_read_b128 v[166:169], v226 offset:7168
	global_load_lds_dwordx4 v[214:215], off
	v_lshl_add_u64 v[214:215], v[210:211], 0, s[26:27]
	s_add_i32 m0, s44, 0xe000
	s_cmp_lg_u32 s28, 0
	global_load_lds_dwordx4 v[214:215], off
	s_cselect_b64 s[34:35], -1, 0
	s_cmp_eq_u32 s28, 0
	s_cbranch_scc0 .Lrx1_2742
